# fast v_rsq/v_rcp replacing IEEE sqrt+div sequences in epilogues, retB gate, dil tail (no other change)
# baseline (speedup 1.0000x reference)
.LBB0_588:
	v_add_u32_e32 v113, v161, v159
	v_sub_u32_e32 v115, v159, v89
	v_sub_u32_e32 v124, v159, v88
	v_sub_u32_e32 v138, v159, v91
	v_sub_u32_e32 v139, v159, v90
	v_sub_u32_e32 v140, v159, v93
	v_sub_u32_e32 v141, v159, v92
	v_sub_u32_e32 v142, v159, v95
	v_sub_u32_e32 v143, v159, v94
	v_cvt_f32_u32_e32 v39, v113
	v_cvt_f32_u32_e32 v40, v124
	v_cvt_f32_u32_e32 v41, v115
	v_cvt_f32_u32_e32 v42, v139
	v_cvt_f32_u32_e32 v43, v138
	v_cvt_f32_u32_e32 v44, v141
	v_cvt_f32_u32_e32 v45, v140
	v_cvt_f32_u32_e32 v46, v143
	v_cvt_f32_u32_e32 v47, v142
	ds_read_b128 v[32:35], v162
	ds_read_b128 v[84:87], v162 offset:32
	ds_read_b128 v[102:105], v162 offset:64
	ds_read_b128 v[106:109], v162 offset:96
	v_add_u32_e32 v36, 0xffffdc00, v160
	v_add_u32_e32 v37, 0xfffffc00, v160
	v_add_u32_e32 v38, 0xffffe000, v160
	ds_read_b64_tr_b16 v[120:121], v36
	ds_read_b64_tr_b16 v[122:123], v36 offset:512
	ds_read_b64_tr_b16 v[116:117], v37
	ds_read_b64_tr_b16 v[118:119], v37 offset:512
	s_waitcnt lgkmcnt(0)
	ds_read_b64_tr_b16 v[130:131], v38
	ds_read_b64_tr_b16 v[132:133], v38 offset:512
	ds_read_b64_tr_b16 v[126:127], v160
	ds_read_b64_tr_b16 v[128:129], v160 offset:512
	s_waitcnt lgkmcnt(0)
	v_mul_f32_e32 v154, v151, v39
	v_mul_f32_e32 v155, v151, v40
	v_mul_f32_e32 v163, v151, v41
	v_mul_f32_e32 v164, v151, v42
	v_mul_f32_e32 v165, v151, v43
	v_mul_f32_e32 v166, v151, v44
	v_mul_f32_e32 v167, v151, v45
	v_mul_f32_e32 v168, v151, v46
	v_mul_f32_e32 v169, v151, v47
	s_waitcnt lgkmcnt(3)
	v_mfma_f32_32x32x16_bf16 v[32:47], v[32:35], v[64:67], 0
	v_add_u32_e32 v152, -1, v113
	v_sub_u32_e32 v144, v159, v97
	v_sub_u32_e32 v145, v159, v96
	v_sub_u32_e32 v146, v159, v99
	v_sub_u32_e32 v147, v159, v98
	v_sub_u32_e32 v148, v159, v101
	v_sub_u32_e32 v149, v159, v100
	s_waitcnt lgkmcnt(2)
	v_mfma_f32_32x32x16_bf16 v[32:47], v[84:87], v[68:71], v[32:47]
	v_cvt_f32_u32_e32 v153, v152
	v_cvt_f32_u32_e32 v110, v145
	v_cvt_f32_u32_e32 v111, v144
	v_cvt_f32_u32_e32 v134, v147
	v_cvt_f32_u32_e32 v135, v146
	v_cvt_f32_u32_e32 v136, v149
	v_cvt_f32_u32_e32 v137, v148
	s_waitcnt lgkmcnt(1)
	v_mfma_f32_32x32x16_bf16 v[32:47], v[102:105], v[72:75], v[32:47]
	v_mul_f32_e32 v153, v151, v153
	v_mul_f32_e32 v170, v151, v110
	v_mul_f32_e32 v171, v151, v111
	v_mul_f32_e32 v173, v151, v134
	v_mul_f32_e32 v174, v151, v135
	v_mul_f32_e32 v136, v151, v136
	v_mul_f32_e32 v137, v151, v137
	s_waitcnt lgkmcnt(0)
	v_mfma_f32_32x32x16_bf16 v[32:47], v[106:109], v[76:79], v[32:47]
	v_exp_f32_e32 v154, v154
	v_exp_f32_e32 v110, v155
	v_exp_f32_e32 v111, v163
	v_exp_f32_e32 v84, v164
	v_exp_f32_e32 v85, v165
	v_exp_f32_e32 v86, v166
	v_exp_f32_e32 v87, v167
	v_exp_f32_e32 v153, v153
	v_exp_f32_e32 v134, v168
	v_exp_f32_e32 v135, v169
	v_exp_f32_e32 v102, v170
	v_exp_f32_e32 v103, v171
	v_exp_f32_e32 v104, v173
	v_exp_f32_e32 v105, v174
	v_exp_f32_e32 v136, v136
	v_exp_f32_e32 v137, v137
	v_mul_f32_e32 v106, v154, v32
	v_mul_f32_e32 v107, v153, v33
	v_cmp_lt_i32_e32 vcc, -1, v152
	v_pk_mul_f32 v[32:33], v[110:111], v[34:35]
	v_pk_mul_f32 v[34:35], v[84:85], v[36:37]
	v_pk_mul_f32 v[36:37], v[86:87], v[38:39]
	v_pk_mul_f32 v[38:39], v[134:135], v[40:41]
	v_pk_mul_f32 v[40:41], v[102:103], v[42:43]
	v_pk_mul_f32 v[42:43], v[104:105], v[44:45]
	v_pk_mul_f32 v[44:45], v[136:137], v[46:47]
	v_cmp_lt_i32_e64 s[0:1], -1, v113
	v_cndmask_b32_e32 v47, 0, v107, vcc
	v_cvt_pk_bf16_f32 v33, v32, v33
	v_cmp_lt_i32_e32 vcc, -1, v124
	v_cvt_pk_bf16_f32 v34, v34, v35
	v_cvt_pk_bf16_f32 v35, v36, v37
	v_cndmask_b32_e64 v46, 0, v106, s[0:1]
	v_cmp_lt_i32_e64 s[0:1], -1, v139
	v_cmp_lt_i32_e64 s[4:5], -1, v141
	v_cvt_pk_bf16_f32 v36, v38, v39
	v_cvt_pk_bf16_f32 v37, v40, v41
	v_cvt_pk_bf16_f32 v39, v44, v45
	v_lshrrev_b32_e32 v40, 16, v34
	v_cmp_lt_i32_e64 s[14:15], -1, v138
	v_lshrrev_b32_e32 v41, 16, v35
	v_cmp_lt_i32_e64 s[16:17], -1, v140
	v_cndmask_b32_e32 v45, 0, v33, vcc
	v_lshrrev_b32_e32 v33, 16, v33
	v_cmp_lt_i32_e32 vcc, -1, v115
	v_cndmask_b32_e64 v34, 0, v34, s[0:1]
	v_cndmask_b32_e64 v35, 0, v35, s[4:5]
	v_cndmask_b32_e32 v33, 0, v33, vcc
	v_cndmask_b32_e64 v40, 0, v40, s[14:15]
	v_cndmask_b32_e64 v41, 0, v41, s[16:17]
	v_cvt_pk_bf16_f32 v32, v46, v47
	v_perm_b32 v33, v33, v45, s3
	v_perm_b32 v34, v40, v34, s3
	v_perm_b32 v35, v41, v35, s3
	v_cmp_lt_i32_e64 s[6:7], -1, v143
	v_cvt_pk_bf16_f32 v38, v42, v43
	v_mfma_f32_32x32x16_bf16 v[0:15], v[120:123], v[32:35], v[0:15]
	v_cmp_lt_i32_e64 s[8:9], -1, v145
	v_cmp_lt_i32_e64 s[10:11], -1, v147
	v_cmp_lt_i32_e64 s[12:13], -1, v149
	v_lshrrev_b32_e32 v42, 16, v37
	v_cmp_lt_i32_e64 s[18:19], -1, v144
	v_lshrrev_b32_e32 v43, 16, v38
	v_cmp_lt_i32_e64 s[20:21], -1, v146
	v_mfma_f32_32x32x16_bf16 v[16:31], v[116:119], v[32:35], v[16:31]
	v_lshrrev_b32_e32 v44, 16, v39
	v_cmp_lt_i32_e64 s[22:23], -1, v148
	v_cndmask_b32_e64 v40, 0, v36, s[6:7]
	v_lshrrev_b32_e32 v36, 16, v36
	v_cmp_lt_i32_e32 vcc, -1, v142
	v_cndmask_b32_e64 v37, 0, v37, s[8:9]
	v_cndmask_b32_e64 v38, 0, v38, s[10:11]
	v_cndmask_b32_e64 v39, 0, v39, s[12:13]
	v_cndmask_b32_e32 v36, 0, v36, vcc
	v_cndmask_b32_e64 v33, 0, v42, s[18:19]
	v_cndmask_b32_e64 v34, 0, v43, s[20:21]
	v_cndmask_b32_e64 v35, 0, v44, s[22:23]
	v_perm_b32 v32, v36, v40, s3
	v_perm_b32 v33, v33, v37, s3
	v_perm_b32 v34, v34, v38, s3
	v_perm_b32 v35, v35, v39, s3
	s_add_i32 s2, s2, -1
	v_subrev_u32_e32 v159, 32, v159
	v_mfma_f32_32x32x16_bf16 v[0:15], v[130:133], v[32:35], v[0:15]
	v_add_u32_e32 v162, 0x1200, v162
	s_cmp_lg_u32 s2, 0
	v_add_u32_e32 v160, 0x800, v160
	v_mfma_f32_32x32x16_bf16 v[16:31], v[126:129], v[32:35], v[16:31]
	s_cbranch_scc1 .LBB0_588
	v_lshlrev_b64 v[32:33], 12, v[82:83]
	v_readlane_b32 s4, v254, 0
	v_lshlrev_b32_e32 v36, 11, v82
	v_and_b32_e32 v32, 0xfff00000, v32
	v_readlane_b32 s6, v254, 2
	v_readlane_b32 s7, v254, 3
	s_waitcnt vmcnt(0)
	v_lshlrev_b32_e32 v40, 16, v62
	v_and_b32_e32 v38, 0xffff0000, v62
	v_lshl_add_u64 v[34:35], s[6:7], 0, v[32:33]
	v_and_b32_e32 v32, 0x7f800, v36
	v_mul_f32_e32 v36, 0xbfb8aa3b, v40
	v_mul_f32_e32 v37, 0xbfb8aa3b, v38
	v_exp_f32_e32 v36, v36
	v_exp_f32_e32 v37, v37
	v_mov_b32_e32 v33, 0
	v_lshl_add_u64 v[34:35], v[34:35], 0, v[32:33]
	v_lshlrev_b32_e32 v45, 16, v61
	v_pk_add_f32 v[36:37], v[36:37], 1.0 op_sel_hi:[1,0]
	v_and_b32_e32 v46, 0xffff0000, v61
	v_lshlrev_b32_e32 v66, 16, v63
	v_and_b32_e32 v44, 0xffff0000, v63
	v_lshlrev_b32_e32 v71, 16, v58
	v_rcp_f32_e32 v32, v37
	s_nop 0
	v_mul_f32_e32 v37, v38, v32
	v_mul_f32_e32 v38, 0xbfb8aa3b, v45
	v_mul_f32_e32 v39, 0xbfb8aa3b, v46
	v_exp_f32_e32 v38, v38
	v_exp_f32_e32 v39, v39
	s_nop 0
	v_pk_add_f32 v[38:39], v[38:39], 1.0 op_sel_hi:[1,0]
	v_rcp_f32_e32 v32, v36
	s_nop 0
	v_mul_f32_e32 v36, v40, v32
	v_and_b32_e32 v58, 0xffff0000, v58
	v_rcp_f32_e32 v32, v39
	s_nop 0
	v_mul_f32_e32 v39, v46, v32
	v_lshlrev_b32_e32 v78, 16, v59
	v_lshlrev_b32_e32 v42, 16, v60
	v_and_b32_e32 v43, 0xffff0000, v60
	v_mul_f32_e32 v40, 0xbfb8aa3b, v42
	v_mul_f32_e32 v41, 0xbfb8aa3b, v43
	v_exp_f32_e32 v40, v40
	v_exp_f32_e32 v41, v41
	v_rcp_f32_e32 v32, v38
	s_nop 0
	v_mul_f32_e32 v38, v45, v32
	v_and_b32_e32 v76, 0xffff0000, v59
	v_lshlrev_b32_e32 v77, 16, v57
	v_pk_add_f32 v[40:41], v[40:41], 1.0 op_sel_hi:[1,0]
	v_and_b32_e32 v57, 0xffff0000, v57
	v_div_scale_f32 v67, s[0:1], v41, v41, v43
	v_rcp_f32_e32 v68, v67
	s_waitcnt lgkmcnt(0)
	s_barrier
	v_rcp_f32_e32 v45, v41
	s_nop 0
	v_mul_f32_e32 v41, v43, v45
	ds_write2_b32 v172, v0, v1 offset1:1
	ds_write2_b32 v172, v2, v3 offset0:2 offset1:3
	ds_write2_b32 v172, v4, v5 offset0:8 offset1:9
	ds_write2_b32 v172, v6, v7 offset0:10 offset1:11
	ds_write2_b32 v172, v8, v9 offset0:16 offset1:17
	ds_write2_b32 v172, v10, v11 offset0:18 offset1:19
	ds_write2_b32 v172, v12, v13 offset0:24 offset1:25
	ds_write2_b32 v172, v14, v15 offset0:26 offset1:27
	ds_write2_b32 v172, v16, v17 offset0:32 offset1:33
	ds_write2_b32 v172, v18, v19 offset0:34 offset1:35
	ds_write2_b32 v172, v20, v21 offset0:40 offset1:41
	ds_write2_b32 v172, v22, v23 offset0:42 offset1:43
	ds_write2_b32 v172, v24, v25 offset0:48 offset1:49
	ds_write2_b32 v172, v26, v27 offset0:50 offset1:51
	ds_write2_b32 v172, v28, v29 offset0:56 offset1:57
	ds_write2_b32 v172, v30, v31 offset0:58 offset1:59
	v_rcp_f32_e32 v43, v40
	s_nop 0
	v_mul_f32_e32 v40, v42, v43
	v_mul_f32_e32 v42, 0xbfb8aa3b, v66
	v_mul_f32_e32 v43, 0xbfb8aa3b, v44
	v_exp_f32_e32 v42, v42
	v_exp_f32_e32 v43, v43
	s_waitcnt lgkmcnt(0)
	s_barrier
	v_pk_add_f32 v[42:43], v[42:43], 1.0 op_sel_hi:[1,0]
	v_lshlrev_b32_e32 v79, 16, v56
	global_load_dwordx4 v[16:19], v[80:81], off offset:48
	global_load_dwordx4 v[20:23], v[80:81], off offset:32
	global_load_dwordx4 v[24:27], v[80:81], off offset:16
	global_load_dwordx4 v[28:31], v[80:81], off
	global_load_dwordx4 v[0:3], v[80:81], off offset:112
	global_load_dwordx4 v[4:7], v[80:81], off offset:96
	global_load_dwordx4 v[8:11], v[80:81], off offset:80
	global_load_dwordx4 v[12:15], v[80:81], off offset:64
	v_and_b32_e32 v80, 0xffff0000, v56
	v_mul_f32_e32 v56, 0xbfb8aa3b, v79
	v_rcp_f32_e32 v45, v43
	s_nop 0
	v_mul_f32_e32 v43, v44, v45
	v_mul_f32_e32 v44, 0xbfb8aa3b, v71
	v_mul_f32_e32 v45, 0xbfb8aa3b, v58
	v_exp_f32_e32 v44, v44
	v_exp_f32_e32 v45, v45
	v_rcp_f32_e32 v67, v42
	s_nop 0
	v_mul_f32_e32 v42, v66, v67
	v_pk_add_f32 v[44:45], v[44:45], 1.0 op_sel_hi:[1,0]
	v_lshlrev_b32_e32 v83, 16, v54
	v_and_b32_e32 v54, 0xffff0000, v54
	v_lshlrev_b32_e32 v113, 16, v55
	v_and_b32_e32 v124, 0xffff0000, v55
	v_rcp_f32_e32 v59, v45
	s_nop 0
	v_mul_f32_e32 v45, v58, v59
	v_mul_f32_e32 v59, 0xbfb8aa3b, v57
	v_mul_f32_e32 v58, 0xbfb8aa3b, v77
	v_exp_f32_e32 v58, v58
	v_exp_f32_e32 v59, v59
	s_nop 0
	v_pk_add_f32 v[58:59], v[58:59], 1.0 op_sel_hi:[1,0]
	v_rcp_f32_e32 v66, v44
	s_nop 0
	v_mul_f32_e32 v44, v71, v66
	v_lshlrev_b32_e32 v88, 16, v53
	v_rcp_f32_e32 v66, v59
	s_nop 0
	v_mul_f32_e32 v57, v57, v66
	v_and_b32_e32 v53, 0xffff0000, v53
	v_exp_f32_e32 v66, v56
	v_mul_f32_e32 v56, 0xbfb8aa3b, v80
	v_exp_f32_e32 v67, v56
	v_rcp_f32_e32 v56, v58
	s_nop 0
	v_mul_f32_e32 v56, v77, v56
	v_lshlrev_b32_e32 v89, 16, v52
	ds_read2_b32 v[46:47], v158 offset0:6 offset1:7
	ds_read2_b32 v[60:61], v158 offset0:4 offset1:5
	ds_read2_b32 v[62:63], v158 offset0:2 offset1:3
	ds_read2_b32 v[64:65], v158 offset1:1
	v_pk_add_f32 v[66:67], v[66:67], 1.0 op_sel_hi:[1,0]
	ds_read2_b32 v[68:69], v158 offset0:14 offset1:15
	ds_read2_b32 v[70:71], v158 offset0:12 offset1:13
	ds_read2_b32 v[72:73], v158 offset0:10 offset1:11
	ds_read2_b32 v[74:75], v158 offset0:8 offset1:9
	s_waitcnt lgkmcnt(4)
	v_add_f32_e32 v32, 0, v64
	v_add_f32_e32 v32, v32, v65
	v_add_f32_e32 v32, v32, v62
	v_rcp_f32_e32 v59, v67
	s_nop 0
	v_mul_f32_e32 v59, v80, v59
	v_add_f32_e32 v32, v32, v63
	v_rcp_f32_e32 v58, v66
	s_nop 0
	v_mul_f32_e32 v58, v79, v58
	v_mul_f32_e32 v66, 0xbfb8aa3b, v78
	v_mul_f32_e32 v67, 0xbfb8aa3b, v76
	v_exp_f32_e32 v66, v66
	v_exp_f32_e32 v67, v67
	v_add_f32_e32 v32, v32, v60
	v_add_f32_e32 v32, v32, v61
	v_add_f32_e32 v32, v32, v46
	v_pk_add_f32 v[66:67], v[66:67], 1.0 op_sel_hi:[1,0]
	v_add_f32_e32 v32, v32, v47
	s_waitcnt lgkmcnt(0)
	v_add_f32_e32 v32, v32, v74
	v_add_f32_e32 v32, v32, v75
	v_add_f32_e32 v32, v32, v72
	v_rcp_f32_e32 v77, v67
	s_nop 0
	v_mul_f32_e32 v67, v76, v77
	v_mul_f32_e32 v76, 0xbfb8aa3b, v83
	v_mul_f32_e32 v77, 0xbfb8aa3b, v54
	v_exp_f32_e32 v76, v76
	v_exp_f32_e32 v77, v77
	v_rcp_f32_e32 v79, v66
	s_nop 0
	v_mul_f32_e32 v66, v78, v79
	v_pk_add_f32 v[76:77], v[76:77], 1.0 op_sel_hi:[1,0]
	v_add_f32_e32 v32, v32, v73
	v_add_f32_e32 v32, v32, v70
	v_add_f32_e32 v32, v32, v71
	v_add_f32_e32 v32, v32, v68
	v_mul_f32_e32 v78, 0xbfb8aa3b, v88
	v_mul_f32_e32 v79, 0xbfb8aa3b, v53
	v_rcp_f32_e32 v55, v77
	s_nop 0
	v_mul_f32_e32 v55, v54, v55
	v_exp_f32_e32 v78, v78
	v_exp_f32_e32 v79, v79
	s_nop 0
	v_pk_add_f32 v[78:79], v[78:79], 1.0 op_sel_hi:[1,0]
	v_rcp_f32_e32 v54, v76
	s_nop 0
	v_mul_f32_e32 v54, v83, v54
	v_add_f32_e32 v32, v32, v69
	v_rcp_f32_e32 v77, v79
	s_nop 0
	v_mul_f32_e32 v77, v53, v77
	s_mov_b32 s37, 0
	v_and_b32_e32 v79, 0xffff0000, v52
	v_mul_f32_e32 v52, 0xbfb8aa3b, v89
	v_mul_f32_e32 v53, 0xbfb8aa3b, v79
	v_exp_f32_e32 v52, v52
	v_exp_f32_e32 v53, v53
	v_rcp_f32_e32 v76, v78
	s_nop 0
	v_mul_f32_e32 v76, v88, v76
	ds_read2_b32 v[80:81], v158 offset0:22 offset1:23
	ds_read2_b32 v[82:83], v158 offset0:20 offset1:21
	ds_read2_b32 v[84:85], v158 offset0:18 offset1:19
	ds_read2_b32 v[86:87], v158 offset0:16 offset1:17
	v_lshl_add_u64 v[34:35], v[34:35], 0, s[36:37]
	v_pk_add_f32 v[52:53], v[52:53], 1.0 op_sel_hi:[1,0]
	v_mov_b32_e32 v115, v33
	s_waitcnt lgkmcnt(0)
	v_add_f32_e32 v32, v32, v86
	v_add_f32_e32 v32, v32, v87
	v_add_f32_e32 v32, v32, v84
	v_rcp_f32_e32 v78, v53
	s_nop 0
	v_mul_f32_e32 v79, v79, v78
	v_add_f32_e32 v32, v32, v85
	v_rcp_f32_e32 v78, v52
	s_nop 0
	v_mul_f32_e32 v78, v89, v78
	v_mul_f32_e32 v52, 0xbfb8aa3b, v113
	v_mul_f32_e32 v53, 0xbfb8aa3b, v124
	v_exp_f32_e32 v52, v52
	v_exp_f32_e32 v53, v53
	v_add_f32_e32 v32, v32, v82
	v_add_f32_e32 v32, v32, v83
	v_add_f32_e32 v32, v32, v80
	v_pk_add_f32 v[88:89], v[52:53], 1.0 op_sel_hi:[1,0]
	ds_read2_b32 v[90:91], v158 offset0:30 offset1:31
	ds_read2_b32 v[52:53], v158 offset0:28 offset1:29
	ds_read2_b32 v[92:93], v158 offset0:26 offset1:27
	ds_read2_b32 v[94:95], v158 offset0:24 offset1:25
	v_add_f32_e32 v32, v32, v81
	s_waitcnt lgkmcnt(0)
	v_add_f32_e32 v32, v32, v94
	v_add_f32_e32 v32, v32, v95
	v_add_f32_e32 v32, v32, v92
	v_add_f32_e32 v32, v32, v93
	v_add_f32_e32 v32, v32, v52
	v_add_f32_e32 v32, v32, v53
	v_add_f32_e32 v32, v32, v90
	v_add_f32_e32 v32, v32, v91
	ds_bpermute_b32 v97, v157, v32
	s_waitcnt lgkmcnt(0)
	v_add_f32_e32 v32, v32, v97
	ds_bpermute_b32 v97, v156, v32
	v_lshl_add_u64 v[34:35], v[34:35], 0, v[114:115]
	s_waitcnt lgkmcnt(0)
	v_add_f32_e32 v32, v32, v97
	v_mul_f32_e32 v32, 0x3c000000, v32
	v_pk_add_f32 v[64:65], v[64:65], v[32:33] op_sel_hi:[1,0] neg_lo:[0,1] neg_hi:[0,1]
	v_pk_add_f32 v[62:63], v[62:63], v[32:33] op_sel_hi:[1,0] neg_lo:[0,1] neg_hi:[0,1]
	v_pk_mul_f32 v[96:97], v[64:65], v[64:65]
	v_pk_mul_f32 v[98:99], v[62:63], v[62:63]
	v_pk_add_f32 v[100:101], v[60:61], v[32:33] op_sel_hi:[1,0] neg_lo:[0,1] neg_hi:[0,1]
	v_pk_add_f32 v[104:105], v[46:47], v[32:33] op_sel_hi:[1,0] neg_lo:[0,1] neg_hi:[0,1]
	v_pk_add_f32 v[74:75], v[74:75], v[32:33] op_sel_hi:[1,0] neg_lo:[0,1] neg_hi:[0,1]
	v_pk_add_f32 v[72:73], v[72:73], v[32:33] op_sel_hi:[1,0] neg_lo:[0,1] neg_hi:[0,1]
	v_pk_add_f32 v[70:71], v[70:71], v[32:33] op_sel_hi:[1,0] neg_lo:[0,1] neg_hi:[0,1]
	v_pk_add_f32 v[68:69], v[68:69], v[32:33] op_sel_hi:[1,0] neg_lo:[0,1] neg_hi:[0,1]
	v_pk_add_f32 v[86:87], v[86:87], v[32:33] op_sel_hi:[1,0] neg_lo:[0,1] neg_hi:[0,1]
	v_pk_add_f32 v[84:85], v[84:85], v[32:33] op_sel_hi:[1,0] neg_lo:[0,1] neg_hi:[0,1]
	v_pk_add_f32 v[82:83], v[82:83], v[32:33] op_sel_hi:[1,0] neg_lo:[0,1] neg_hi:[0,1]
	v_pk_add_f32 v[80:81], v[80:81], v[32:33] op_sel_hi:[1,0] neg_lo:[0,1] neg_hi:[0,1]
	v_pk_add_f32 v[94:95], v[94:95], v[32:33] op_sel_hi:[1,0] neg_lo:[0,1] neg_hi:[0,1]
	v_pk_add_f32 v[60:61], v[92:93], v[32:33] op_sel_hi:[1,0] neg_lo:[0,1] neg_hi:[0,1]
	v_pk_add_f32 v[52:53], v[52:53], v[32:33] op_sel_hi:[1,0] neg_lo:[0,1] neg_hi:[0,1]
	v_pk_add_f32 v[46:47], v[90:91], v[32:33] op_sel_hi:[1,0] neg_lo:[0,1] neg_hi:[0,1]
	v_add_f32_e32 v32, v96, v97
	v_add_f32_e32 v32, v98, v32
	v_pk_mul_f32 v[102:103], v[100:101], v[100:101]
	v_add_f32_e32 v32, v99, v32
	v_add_f32_e32 v32, v102, v32
	v_pk_mul_f32 v[106:107], v[104:105], v[104:105]
	v_add_f32_e32 v32, v103, v32
	v_add_f32_e32 v32, v106, v32
	v_pk_mul_f32 v[108:109], v[74:75], v[74:75]
	v_add_f32_e32 v32, v107, v32
	v_add_f32_e32 v32, v108, v32
	v_pk_mul_f32 v[110:111], v[72:73], v[72:73]
	v_add_f32_e32 v32, v109, v32
	v_add_f32_e32 v32, v110, v32
	v_pk_mul_f32 v[114:115], v[70:71], v[70:71]
	v_add_f32_e32 v32, v111, v32
	v_add_f32_e32 v32, v114, v32
	v_pk_mul_f32 v[116:117], v[68:69], v[68:69]
	v_add_f32_e32 v32, v115, v32
	v_add_f32_e32 v32, v116, v32
	v_pk_mul_f32 v[118:119], v[86:87], v[86:87]
	v_add_f32_e32 v32, v117, v32
	v_add_f32_e32 v32, v118, v32
	v_pk_mul_f32 v[120:121], v[84:85], v[84:85]
	v_add_f32_e32 v32, v119, v32
	v_add_f32_e32 v32, v120, v32
	v_pk_mul_f32 v[122:123], v[82:83], v[82:83]
	v_add_f32_e32 v32, v121, v32
	v_add_f32_e32 v32, v122, v32
	v_pk_mul_f32 v[126:127], v[80:81], v[80:81]
	v_add_f32_e32 v32, v123, v32
	v_add_f32_e32 v32, v126, v32
	v_pk_mul_f32 v[128:129], v[94:95], v[94:95]
	v_add_f32_e32 v32, v127, v32
	v_add_f32_e32 v32, v128, v32
	v_pk_mul_f32 v[92:93], v[60:61], v[60:61]
	v_add_f32_e32 v32, v129, v32
	v_add_f32_e32 v32, v92, v32
	v_pk_mul_f32 v[130:131], v[52:53], v[52:53]
	v_add_f32_e32 v32, v93, v32
	v_add_f32_e32 v32, v130, v32
	v_pk_mul_f32 v[90:91], v[46:47], v[46:47]
	v_add_f32_e32 v32, v131, v32
	v_add_f32_e32 v32, v90, v32
	v_add_f32_e32 v32, v91, v32
	ds_bpermute_b32 v90, v157, v32
	s_mov_b32 s0, 0xf800000
	v_rcp_f32_e32 v91, v89
	s_nop 0
	v_mul_f32_e32 v89, v124, v91
	s_waitcnt lgkmcnt(0)
	v_add_f32_e32 v32, v32, v90
	ds_bpermute_b32 v90, v156, v32
	s_waitcnt lgkmcnt(0)
	v_add_f32_e32 v32, v32, v90
	v_mov_b32_e32 v90, 0x358637bd
	v_fmac_f32_e32 v90, 0x3c000000, v32
	v_mul_f32_e32 v32, 0x4f800000, v90
	v_cmp_gt_f32_e64 s[0:1], s0, v90
	s_nop 1
	v_cndmask_b32_e64 v32, v90, v32, s[0:1]
	v_sqrt_f32_e32 v90, v32
	v_readlane_b32 s5, v254, 1
	v_add_u32_e32 v93, -1, v90
	v_fma_f32 v96, -v93, v90, v32
	v_cmp_ge_f32_e64 s[4:5], 0, v96
	v_add_u32_e32 v96, 1, v90
	s_nop 1
	v_cndmask_b32_e64 v93, v90, v93, s[4:5]
	v_fma_f32 v90, -v96, v90, v32
	v_cmp_lt_f32_e64 s[4:5], 0, v90
	v_rcp_f32_e32 v91, v88
	s_nop 0
	v_mul_f32_e32 v88, v113, v91
	s_movk_i32 s2, 0x37ff
	v_cndmask_b32_e64 v90, v93, v96, s[4:5]
	v_mul_f32_e32 v93, 0x37800000, v90
	v_cndmask_b32_e64 v90, v90, v93, s[0:1]
	v_mov_b32_e32 v93, 0x260
	v_cmp_class_f32_e64 s[0:1], v32, v93
	s_nop 1
	v_cndmask_b32_e64 v32, v90, v32, s[0:1]
	v_rcp_f32_e32 v32, v32
	s_nop 0
	v_pk_mul_f32 v[64:65], v[64:65], v[32:33] op_sel_hi:[1,0]
	s_waitcnt vmcnt(4)
	v_pk_mul_f32 v[28:29], v[28:29], v[64:65]
	s_nop 0
	v_pk_mul_f32 v[28:29], v[40:41], v[28:29]
	v_pk_mul_f32 v[40:41], v[62:63], v[32:33] op_sel_hi:[1,0]
	s_nop 0
	v_pk_mul_f32 v[30:31], v[30:31], v[40:41]
	s_nop 0
	v_pk_mul_f32 v[30:31], v[38:39], v[30:31]
	v_pk_mul_f32 v[38:39], v[100:101], v[32:33] op_sel_hi:[1,0]
	s_nop 0
	v_pk_mul_f32 v[24:25], v[24:25], v[38:39]
	s_nop 0
	v_pk_mul_f32 v[36:37], v[36:37], v[24:25]
	v_pk_mul_f32 v[24:25], v[104:105], v[32:33] op_sel_hi:[1,0]
	s_nop 0
	v_pk_mul_f32 v[24:25], v[26:27], v[24:25]
	v_cvt_pk_bf16_f32 v26, v36, v37
	v_pk_mul_f32 v[38:39], v[42:43], v[24:25]
	v_cvt_pk_bf16_f32 v24, v28, v29
	v_cvt_pk_bf16_f32 v25, v30, v31
	v_cvt_pk_bf16_f32 v27, v38, v39
	global_store_dwordx4 v[34:35], v[24:27], off
	s_nop 1
	v_pk_mul_f32 v[24:25], v[74:75], v[32:33] op_sel_hi:[1,0]
	s_nop 0
	v_pk_mul_f32 v[20:21], v[20:21], v[24:25]
	v_pk_mul_f32 v[24:25], v[72:73], v[32:33] op_sel_hi:[1,0]
	v_pk_mul_f32 v[20:21], v[58:59], v[20:21]
	v_pk_mul_f32 v[22:23], v[22:23], v[24:25]
	v_pk_mul_f32 v[24:25], v[70:71], v[32:33] op_sel_hi:[1,0]
	v_pk_mul_f32 v[22:23], v[56:57], v[22:23]
	v_pk_mul_f32 v[16:17], v[16:17], v[24:25]
	s_nop 0
	v_pk_mul_f32 v[24:25], v[44:45], v[16:17]
	v_pk_mul_f32 v[16:17], v[68:69], v[32:33] op_sel_hi:[1,0]
	s_nop 0
	v_pk_mul_f32 v[16:17], v[18:19], v[16:17]
	v_cvt_pk_bf16_f32 v18, v24, v25
	v_pk_mul_f32 v[26:27], v[66:67], v[16:17]
	v_cvt_pk_bf16_f32 v16, v20, v21
	v_cvt_pk_bf16_f32 v17, v22, v23
	v_cvt_pk_bf16_f32 v19, v26, v27
	global_store_dwordx4 v[34:35], v[16:19], off offset:16
	v_lshlrev_b32_e32 v20, 16, v48
	v_and_b32_e32 v21, 0xffff0000, v48
	v_pk_mul_f32 v[16:17], v[86:87], v[32:33] op_sel_hi:[1,0]
	s_waitcnt vmcnt(2)
	v_pk_mul_f32 v[12:13], v[12:13], v[16:17]
	v_pk_mul_f32 v[16:17], v[84:85], v[32:33] op_sel_hi:[1,0]
	v_pk_mul_f32 v[12:13], v[78:79], v[12:13]
	v_pk_mul_f32 v[14:15], v[14:15], v[16:17]
	v_pk_mul_f32 v[16:17], v[82:83], v[32:33] op_sel_hi:[1,0]
	v_pk_mul_f32 v[14:15], v[76:77], v[14:15]
	v_pk_mul_f32 v[8:9], v[8:9], v[16:17]
	s_nop 0
	v_pk_mul_f32 v[16:17], v[54:55], v[8:9]
	v_pk_mul_f32 v[8:9], v[80:81], v[32:33] op_sel_hi:[1,0]
	s_nop 0
	v_pk_mul_f32 v[8:9], v[10:11], v[8:9]
	v_mul_f32_e32 v10, 0xbfb8aa3b, v20
	v_mul_f32_e32 v11, 0xbfb8aa3b, v21
	v_exp_f32_e32 v10, v10
	v_exp_f32_e32 v11, v11
	v_pk_mul_f32 v[18:19], v[88:89], v[8:9]
	v_cvt_pk_bf16_f32 v8, v12, v13
	v_cvt_pk_bf16_f32 v9, v14, v15
	v_pk_add_f32 v[12:13], v[10:11], 1.0 op_sel_hi:[1,0]
	v_cvt_pk_bf16_f32 v10, v16, v17
	v_cvt_pk_bf16_f32 v11, v18, v19
	global_store_dwordx4 v[34:35], v[8:11], off offset:32
	v_and_b32_e32 v16, 0xffff0000, v49
	s_nop 0
	v_rcp_f32_e32 v9, v13
	s_nop 0
	v_mul_f32_e32 v9, v21, v9
	v_lshlrev_b32_e32 v15, 16, v49
	v_mul_f32_e32 v10, 0xbfb8aa3b, v15
	v_mul_f32_e32 v11, 0xbfb8aa3b, v16
	v_exp_f32_e32 v10, v10
	v_exp_f32_e32 v11, v11
	v_rcp_f32_e32 v8, v12
	s_nop 0
	v_mul_f32_e32 v8, v20, v8
	v_pk_mul_f32 v[12:13], v[94:95], v[32:33] op_sel_hi:[1,0]
	v_pk_add_f32 v[10:11], v[10:11], 1.0 op_sel_hi:[1,0]
	v_pk_mul_f32 v[4:5], v[4:5], v[12:13]
	v_pk_mul_f32 v[4:5], v[8:9], v[4:5]
	v_rcp_f32_e32 v9, v11
	s_nop 0
	v_mul_f32_e32 v9, v16, v9
	v_lshlrev_b32_e32 v16, 16, v50
	v_and_b32_e32 v17, 0xffff0000, v50
	v_mul_f32_e32 v12, 0xbfb8aa3b, v16
	v_mul_f32_e32 v13, 0xbfb8aa3b, v17
	v_exp_f32_e32 v12, v12
	v_exp_f32_e32 v13, v13
	v_rcp_f32_e32 v8, v10
	s_nop 0
	v_mul_f32_e32 v8, v15, v8
	v_pk_add_f32 v[10:11], v[12:13], 1.0 op_sel_hi:[1,0]
	s_nop 0
	v_pk_mul_f32 v[12:13], v[60:61], v[32:33] op_sel_hi:[1,0]
	s_nop 0
	v_pk_mul_f32 v[6:7], v[6:7], v[12:13]
	s_nop 0
	v_pk_mul_f32 v[6:7], v[8:9], v[6:7]
	v_rcp_f32_e32 v9, v11
	s_nop 0
	v_mul_f32_e32 v9, v17, v9
	v_lshlrev_b32_e32 v15, 16, v51
	v_and_b32_e32 v17, 0xffff0000, v51
	v_mul_f32_e32 v12, 0xbfb8aa3b, v15
	v_mul_f32_e32 v13, 0xbfb8aa3b, v17
	v_exp_f32_e32 v12, v12
	v_exp_f32_e32 v13, v13
	v_rcp_f32_e32 v8, v10
	s_nop 0
	v_mul_f32_e32 v8, v16, v8
	v_pk_add_f32 v[10:11], v[12:13], 1.0 op_sel_hi:[1,0]
	s_nop 0
	v_pk_mul_f32 v[12:13], v[52:53], v[32:33] op_sel_hi:[1,0]
	s_nop 0
	v_pk_mul_f32 v[0:1], v[0:1], v[12:13]
	s_nop 0
	v_pk_mul_f32 v[8:9], v[8:9], v[0:1]
	v_rcp_f32_e32 v1, v11
	s_nop 0
	v_mul_f32_e32 v1, v17, v1
	v_rcp_f32_e32 v0, v10
	s_nop 0
	v_mul_f32_e32 v0, v15, v0
	v_pk_mul_f32 v[10:11], v[46:47], v[32:33] op_sel_hi:[1,0]
	s_mov_b64 s[0:1], 0x3300000
	v_pk_mul_f32 v[2:3], v[2:3], v[10:11]
	s_nop 0
	v_pk_mul_f32 v[10:11], v[0:1], v[2:3]
	v_cvt_pk_bf16_f32 v0, v4, v5
	v_cvt_pk_bf16_f32 v1, v6, v7
	v_cvt_pk_bf16_f32 v2, v8, v9
	v_cvt_pk_bf16_f32 v3, v10, v11
	global_store_dwordx4 v[34:35], v[0:3], off offset:48
	v_lshl_add_u32 v5, s52, 9, v226
	s_waitcnt lgkmcnt(0)
	s_barrier
	v_bfe_u32 v2, v226, 3, 3
	v_lshlrev_b32_e32 v32, 2, v2
	v_lshl_add_u64 v[0:1], s[96:97], 0, v[32:33]
	v_lshlrev_b32_e32 v32, 7, v2
	v_lshl_add_u64 v[0:1], v[0:1], 0, s[0:1]
	v_lshlrev_b32_e32 v4, 6, v2
	v_lshl_add_u64 v[2:3], s[96:97], 0, v[32:33]
	s_mov_b64 s[0:1], 0xb500000
	v_lshl_add_u64 v[2:3], v[2:3], 0, s[0:1]
	s_lshl_b32 s0, s88, 6
	v_add_u32_e32 v6, 0xfffff800, v5
	v_lshrrev_b32_e32 v5, 6, v5
	s_and_b32 s0, s0, 0xfffff800
	v_lshlrev_b32_e32 v8, 10, v5
	v_or_b32_e32 v5, s0, v5
	v_lshl_add_u32 v7, s52, 12, v230
	v_lshl_or_b32 v32, s53, 8, v5
	s_mov_b64 s[0:1], 0
	v_lshlrev_b32_e32 v4, 1, v4

.LBB0_664:
	v_lshl_add_u32 v128, s64, 8, v139
	v_ashrrev_i32_e32 v129, 31, v128
	v_lshl_add_u64 v[166:167], v[128:129], 2, s[12:13]
	v_or_b32_e32 v136, 16, v128
	global_load_dword v170, v[166:167], off
	v_ashrrev_i32_e32 v137, 31, v136
	v_lshl_add_u64 v[130:131], v[136:137], 2, s[12:13]
	global_load_dword v171, v[130:131], off
	v_or_b32_e32 v134, 32, v128
	v_or_b32_e32 v130, 48, v128
	v_ashrrev_i32_e32 v135, 31, v134
	v_ashrrev_i32_e32 v131, 31, v130
	v_lshl_add_u64 v[164:165], v[134:135], 2, s[12:13]
	v_lshl_add_u64 v[168:169], v[130:131], 2, s[12:13]
	global_load_dword v150, v[166:167], off offset:512
	global_load_dword v149, v[166:167], off offset:576
	global_load_dword v148, v[166:167], off offset:640
	s_nop 0
	global_load_dword v164, v[164:165], off
	s_nop 0
	global_load_dword v151, v[168:169], off
	global_load_dword v147, v[166:167], off offset:704
	v_lshl_or_b32 v132, s33, 8, v141
	v_ashrrev_i32_e32 v133, 31, v132
	v_lshlrev_b64 v[128:129], 13, v[128:129]
	v_lshlrev_b64 v[132:133], 1, v[132:133]
	v_lshl_add_u64 v[128:129], s[14:15], 0, v[128:129]
	v_lshl_add_u64 v[128:129], v[128:129], 0, v[132:133]
	s_cmp_eq_u32 s63, 3
	s_waitcnt vmcnt(0)
	v_fmamk_f32 v165, v170, 0x3a800000, v145
	v_fmamk_f32 v167, v171, 0x3a800000, v145
	v_rsq_f32_e32 v165, v165
	v_rsq_f32_e32 v171, v167
	v_mov_b32_e32 v166, v165
	v_pk_fma_f32 v[126:127], v[126:127], v[166:167], 0 op_sel_hi:[1,0,0]
	v_pk_fma_f32 v[124:125], v[124:125], v[166:167], 0 op_sel_hi:[1,0,0]
	v_pk_fma_f32 v[122:123], v[122:123], v[166:167], 0 op_sel_hi:[1,0,0]
	v_pk_fma_f32 v[120:121], v[120:121], v[166:167], 0 op_sel_hi:[1,0,0]
	v_pk_fma_f32 v[114:115], v[114:115], v[166:167], 0 op_sel_hi:[1,0,0]
	v_pk_fma_f32 v[112:113], v[112:113], v[166:167], 0 op_sel_hi:[1,0,0]
	v_max_f32_e32 v124, 0, v124
	v_max_f32_e32 v120, 0, v120
	v_max_f32_e32 v125, 0, v125
	v_max_f32_e32 v121, 0, v121
	v_max_f32_e32 v126, 0, v126
	v_max_f32_e32 v122, 0, v122
	v_max_f32_e32 v127, 0, v127
	v_max_f32_e32 v123, 0, v123
	v_max_f32_e32 v112, 0, v112
	v_max_f32_e32 v113, 0, v113
	v_max_f32_e32 v114, 0, v114
	v_max_f32_e32 v115, 0, v115
	v_pk_mul_f32 v[124:125], v[124:125], v[124:125]
	v_pk_mul_f32 v[120:121], v[120:121], v[120:121]
	v_pk_mul_f32 v[126:127], v[126:127], v[126:127]
	v_pk_mul_f32 v[122:123], v[122:123], v[122:123]
	v_pk_fma_f32 v[118:119], v[118:119], v[166:167], 0 op_sel_hi:[1,0,0]
	v_pk_fma_f32 v[116:117], v[116:117], v[166:167], 0 op_sel_hi:[1,0,0]
	v_pk_mul_f32 v[166:167], v[112:113], v[112:113]
	v_pk_mul_f32 v[168:169], v[114:115], v[114:115]
	v_cvt_pk_bf16_f32 v112, v124, v125
	v_cvt_pk_bf16_f32 v113, v126, v127
	v_cvt_pk_bf16_f32 v114, v120, v121
	v_cvt_pk_bf16_f32 v115, v122, v123
	global_store_dwordx4 v[128:129], v[112:115], off
	v_max_f32_e32 v116, 0, v116
	v_max_f32_e32 v117, 0, v117
	v_max_f32_e32 v118, 0, v118
	v_max_f32_e32 v119, 0, v119
	v_pk_mul_f32 v[116:117], v[116:117], v[116:117]
	v_mov_b32_e32 v112, v171
	v_pk_mul_f32 v[118:119], v[118:119], v[118:119]
	v_pk_fma_f32 v[104:105], v[104:105], v[112:113], 0 op_sel_hi:[1,0,0]
	v_cvt_pk_bf16_f32 v116, v116, v117
	v_cvt_pk_bf16_f32 v117, v118, v119
	v_cvt_pk_bf16_f32 v118, v166, v167
	v_cvt_pk_bf16_f32 v119, v168, v169
	v_pk_fma_f32 v[110:111], v[110:111], v[112:113], 0 op_sel_hi:[1,0,0]
	v_pk_fma_f32 v[108:109], v[108:109], v[112:113], 0 op_sel_hi:[1,0,0]
	v_pk_fma_f32 v[106:107], v[106:107], v[112:113], 0 op_sel_hi:[1,0,0]
	v_max_f32_e32 v104, 0, v104
	v_max_f32_e32 v105, 0, v105
	global_store_dwordx4 v[128:129], v[116:119], off offset:256
	v_lshlrev_b64 v[114:115], 13, v[136:137]
	v_max_f32_e32 v108, 0, v108
	v_max_f32_e32 v109, 0, v109
	v_pk_mul_f32 v[116:117], v[104:105], v[104:105]
	v_max_f32_e32 v104, 0, v110
	v_max_f32_e32 v106, 0, v106
	v_max_f32_e32 v105, 0, v111
	v_max_f32_e32 v107, 0, v107
	v_lshl_add_u64 v[114:115], s[14:15], 0, v[114:115]
	v_pk_mul_f32 v[108:109], v[108:109], v[108:109]
	v_pk_mul_f32 v[110:111], v[104:105], v[104:105]
	v_pk_mul_f32 v[118:119], v[106:107], v[106:107]
	v_pk_fma_f32 v[96:97], v[96:97], v[112:113], 0 op_sel_hi:[1,0,0]
	v_lshl_add_u64 v[114:115], v[114:115], 0, v[132:133]
	v_cvt_pk_bf16_f32 v104, v108, v109
	v_cvt_pk_bf16_f32 v105, v110, v111
	v_cvt_pk_bf16_f32 v106, v116, v117
	v_cvt_pk_bf16_f32 v107, v118, v119
	v_pk_fma_f32 v[102:103], v[102:103], v[112:113], 0 op_sel_hi:[1,0,0]
	v_max_f32_e32 v96, 0, v96
	v_max_f32_e32 v97, 0, v97
	global_store_dwordx4 v[114:115], v[104:107], off
	v_pk_fma_f32 v[98:99], v[98:99], v[112:113], 0 op_sel_hi:[1,0,0]
	v_pk_fma_f32 v[100:101], v[100:101], v[112:113], 0 op_sel_hi:[1,0,0]
	v_pk_mul_f32 v[104:105], v[96:97], v[96:97]
	v_max_f32_e32 v96, 0, v102
	v_max_f32_e32 v97, 0, v103
	v_pk_mul_f32 v[102:103], v[96:97], v[96:97]
	v_fmamk_f32 v96, v164, 0x3a800000, v145
	v_max_f32_e32 v98, 0, v98
	v_max_f32_e32 v99, 0, v99
	v_rsq_f32_e32 v108, v96
	v_pk_mul_f32 v[106:107], v[98:99], v[98:99]
	v_max_f32_e32 v100, 0, v100
	v_max_f32_e32 v101, 0, v101
	v_pk_mul_f32 v[100:101], v[100:101], v[100:101]
	v_cvt_pk_bf16_f32 v96, v100, v101
	v_cvt_pk_bf16_f32 v97, v102, v103
	s_nop 0
	v_cvt_pk_bf16_f32 v99, v106, v107
	s_nop 0
	v_mov_b32_e32 v100, v108
	v_cvt_pk_bf16_f32 v98, v104, v105
	global_store_dwordx4 v[114:115], v[96:99], off offset:256
	s_nop 1
	v_mov_b32_e32 v96, v100
	v_pk_fma_f32 v[88:89], v[88:89], v[96:97], 0 op_sel_hi:[1,0,0]
	v_pk_fma_f32 v[94:95], v[94:95], v[96:97], 0 op_sel_hi:[1,0,0]
	v_pk_fma_f32 v[92:93], v[92:93], v[96:97], 0 op_sel_hi:[1,0,0]
	v_pk_fma_f32 v[90:91], v[90:91], v[96:97], 0 op_sel_hi:[1,0,0]
	v_max_f32_e32 v88, 0, v88
	v_max_f32_e32 v89, 0, v89
	v_lshlrev_b64 v[98:99], 13, v[134:135]
	v_max_f32_e32 v92, 0, v92
	v_max_f32_e32 v93, 0, v93
	v_pk_mul_f32 v[100:101], v[88:89], v[88:89]
	v_max_f32_e32 v88, 0, v94
	v_max_f32_e32 v90, 0, v90
	v_max_f32_e32 v89, 0, v95
	v_max_f32_e32 v91, 0, v91
	v_lshl_add_u64 v[98:99], s[14:15], 0, v[98:99]
	v_pk_mul_f32 v[92:93], v[92:93], v[92:93]
	v_pk_mul_f32 v[94:95], v[88:89], v[88:89]
	v_pk_mul_f32 v[102:103], v[90:91], v[90:91]
	v_pk_fma_f32 v[80:81], v[80:81], v[96:97], 0 op_sel_hi:[1,0,0]
	v_lshl_add_u64 v[98:99], v[98:99], 0, v[132:133]
	v_cvt_pk_bf16_f32 v88, v92, v93
	v_cvt_pk_bf16_f32 v89, v94, v95
	v_cvt_pk_bf16_f32 v90, v100, v101
	v_cvt_pk_bf16_f32 v91, v102, v103
	v_pk_fma_f32 v[86:87], v[86:87], v[96:97], 0 op_sel_hi:[1,0,0]
	v_max_f32_e32 v80, 0, v80
	v_max_f32_e32 v81, 0, v81
	global_store_dwordx4 v[98:99], v[88:91], off
	v_pk_fma_f32 v[82:83], v[82:83], v[96:97], 0 op_sel_hi:[1,0,0]
	v_pk_fma_f32 v[84:85], v[84:85], v[96:97], 0 op_sel_hi:[1,0,0]
	v_pk_mul_f32 v[88:89], v[80:81], v[80:81]
	v_max_f32_e32 v80, 0, v86
	v_max_f32_e32 v81, 0, v87
	v_pk_mul_f32 v[86:87], v[80:81], v[80:81]
	v_fmamk_f32 v80, v151, 0x3a800000, v145
	v_max_f32_e32 v82, 0, v82
	v_max_f32_e32 v83, 0, v83
	v_rsq_f32_e32 v92, v80
	v_pk_mul_f32 v[90:91], v[82:83], v[82:83]
	v_max_f32_e32 v84, 0, v84
	v_max_f32_e32 v85, 0, v85
	v_pk_mul_f32 v[84:85], v[84:85], v[84:85]
	v_cvt_pk_bf16_f32 v80, v84, v85
	v_cvt_pk_bf16_f32 v81, v86, v87
	s_nop 0
	v_cvt_pk_bf16_f32 v83, v90, v91
	s_nop 0
	v_mov_b32_e32 v84, v92
	v_cvt_pk_bf16_f32 v82, v88, v89
	global_store_dwordx4 v[98:99], v[80:83], off offset:256
	s_nop 1
	v_mov_b32_e32 v80, v84
	v_pk_fma_f32 v[72:73], v[72:73], v[80:81], 0 op_sel_hi:[1,0,0]
	v_pk_fma_f32 v[78:79], v[78:79], v[80:81], 0 op_sel_hi:[1,0,0]
	v_pk_fma_f32 v[76:77], v[76:77], v[80:81], 0 op_sel_hi:[1,0,0]
	v_pk_fma_f32 v[74:75], v[74:75], v[80:81], 0 op_sel_hi:[1,0,0]
	v_max_f32_e32 v72, 0, v72
	v_max_f32_e32 v73, 0, v73
	v_lshlrev_b64 v[82:83], 13, v[130:131]
	v_max_f32_e32 v76, 0, v76
	v_max_f32_e32 v77, 0, v77
	v_pk_mul_f32 v[84:85], v[72:73], v[72:73]
	v_max_f32_e32 v72, 0, v78
	v_max_f32_e32 v74, 0, v74
	v_max_f32_e32 v73, 0, v79
	v_max_f32_e32 v75, 0, v75
	v_lshl_add_u64 v[82:83], s[14:15], 0, v[82:83]
	v_pk_mul_f32 v[76:77], v[76:77], v[76:77]
	v_pk_mul_f32 v[78:79], v[72:73], v[72:73]
	v_pk_mul_f32 v[86:87], v[74:75], v[74:75]
	v_pk_fma_f32 v[64:65], v[64:65], v[80:81], 0 op_sel_hi:[1,0,0]
	v_lshl_add_u64 v[82:83], v[82:83], 0, v[132:133]
	v_cvt_pk_bf16_f32 v72, v76, v77
	v_cvt_pk_bf16_f32 v73, v78, v79
	v_cvt_pk_bf16_f32 v74, v84, v85
	v_cvt_pk_bf16_f32 v75, v86, v87
	v_pk_fma_f32 v[70:71], v[70:71], v[80:81], 0 op_sel_hi:[1,0,0]
	v_max_f32_e32 v64, 0, v64
	v_max_f32_e32 v65, 0, v65
	global_store_dwordx4 v[82:83], v[72:75], off
	v_pk_fma_f32 v[66:67], v[66:67], v[80:81], 0 op_sel_hi:[1,0,0]
	v_pk_fma_f32 v[68:69], v[68:69], v[80:81], 0 op_sel_hi:[1,0,0]
	v_pk_mul_f32 v[72:73], v[64:65], v[64:65]
	v_max_f32_e32 v64, 0, v70
	v_max_f32_e32 v65, 0, v71
	v_pk_mul_f32 v[70:71], v[64:65], v[64:65]
	v_fmamk_f32 v64, v150, 0x3a800000, v145
	v_max_f32_e32 v66, 0, v66
	v_max_f32_e32 v67, 0, v67
	v_rsq_f32_e32 v76, v64
	v_pk_mul_f32 v[74:75], v[66:67], v[66:67]
	v_max_f32_e32 v68, 0, v68
	v_max_f32_e32 v69, 0, v69
	v_pk_mul_f32 v[68:69], v[68:69], v[68:69]
	v_cvt_pk_bf16_f32 v64, v68, v69
	v_cvt_pk_bf16_f32 v65, v70, v71
	s_nop 0
	v_cvt_pk_bf16_f32 v67, v74, v75
	s_nop 0
	v_mov_b32_e32 v68, v76
	v_cvt_pk_bf16_f32 v66, v72, v73
	global_store_dwordx4 v[82:83], v[64:67], off offset:256
	s_mov_b64 s[0:1], 0x100000
	s_nop 0
	v_mov_b32_e32 v64, v68
	v_pk_fma_f32 v[60:61], v[60:61], v[64:65], 0 op_sel_hi:[1,0,0]
	v_pk_fma_f32 v[56:57], v[56:57], v[64:65], 0 op_sel_hi:[1,0,0]
	v_pk_fma_f32 v[62:63], v[62:63], v[64:65], 0 op_sel_hi:[1,0,0]
	v_pk_fma_f32 v[58:59], v[58:59], v[64:65], 0 op_sel_hi:[1,0,0]
	v_max_f32_e32 v60, 0, v60
	v_max_f32_e32 v56, 0, v56
	v_max_f32_e32 v61, 0, v61
	v_max_f32_e32 v57, 0, v57
	v_lshl_add_u64 v[66:67], v[128:129], 0, s[0:1]
	v_pk_mul_f32 v[60:61], v[60:61], v[60:61]
	v_pk_mul_f32 v[68:69], v[56:57], v[56:57]
	v_max_f32_e32 v56, 0, v62
	v_max_f32_e32 v58, 0, v58
	v_max_f32_e32 v57, 0, v63
	v_max_f32_e32 v59, 0, v59
	s_mov_b32 s0, 0x100000
	v_pk_mul_f32 v[62:63], v[56:57], v[56:57]
	v_pk_mul_f32 v[70:71], v[58:59], v[58:59]
	v_cvt_pk_bf16_f32 v56, v60, v61
	v_add_co_u32_e32 v60, vcc, s0, v128
	v_pk_fma_f32 v[48:49], v[48:49], v[64:65], 0 op_sel_hi:[1,0,0]
	v_cvt_pk_bf16_f32 v57, v62, v63
	v_cvt_pk_bf16_f32 v58, v68, v69
	v_cvt_pk_bf16_f32 v59, v70, v71
	v_addc_co_u32_e32 v61, vcc, 0, v129, vcc
	v_pk_fma_f32 v[54:55], v[54:55], v[64:65], 0 op_sel_hi:[1,0,0]
	v_max_f32_e32 v48, 0, v48
	v_max_f32_e32 v49, 0, v49
	global_store_dwordx4 v[60:61], v[56:59], off
	v_pk_fma_f32 v[50:51], v[50:51], v[64:65], 0 op_sel_hi:[1,0,0]
	v_pk_fma_f32 v[52:53], v[52:53], v[64:65], 0 op_sel_hi:[1,0,0]
	v_pk_mul_f32 v[56:57], v[48:49], v[48:49]
	v_max_f32_e32 v48, 0, v54
	v_max_f32_e32 v49, 0, v55
	v_pk_mul_f32 v[54:55], v[48:49], v[48:49]
	v_fmamk_f32 v48, v149, 0x3a800000, v145
	v_max_f32_e32 v50, 0, v50
	v_max_f32_e32 v51, 0, v51
	v_rsq_f32_e32 v60, v48
	v_pk_mul_f32 v[58:59], v[50:51], v[50:51]
	v_max_f32_e32 v52, 0, v52
	v_max_f32_e32 v53, 0, v53
	v_pk_mul_f32 v[52:53], v[52:53], v[52:53]
	v_cvt_pk_bf16_f32 v48, v52, v53
	v_cvt_pk_bf16_f32 v49, v54, v55
	s_nop 0
	v_cvt_pk_bf16_f32 v51, v58, v59
	s_nop 0
	v_mov_b32_e32 v52, v60
	v_cvt_pk_bf16_f32 v50, v56, v57
	global_store_dwordx4 v[66:67], v[48:51], off offset:256
	s_mov_b64 s[0:1], 0x120000
	s_nop 0
	v_mov_b32_e32 v48, v52
	v_pk_fma_f32 v[44:45], v[44:45], v[48:49], 0 op_sel_hi:[1,0,0]
	v_pk_fma_f32 v[40:41], v[40:41], v[48:49], 0 op_sel_hi:[1,0,0]
	v_pk_fma_f32 v[46:47], v[46:47], v[48:49], 0 op_sel_hi:[1,0,0]
	v_pk_fma_f32 v[42:43], v[42:43], v[48:49], 0 op_sel_hi:[1,0,0]
	v_max_f32_e32 v44, 0, v44
	v_max_f32_e32 v40, 0, v40
	v_max_f32_e32 v45, 0, v45
	v_max_f32_e32 v41, 0, v41
	v_lshl_add_u64 v[50:51], v[128:129], 0, s[0:1]
	v_pk_mul_f32 v[44:45], v[44:45], v[44:45]
	v_pk_mul_f32 v[52:53], v[40:41], v[40:41]
	v_max_f32_e32 v40, 0, v46
	v_max_f32_e32 v42, 0, v42
	v_max_f32_e32 v41, 0, v47
	v_max_f32_e32 v43, 0, v43
	s_mov_b32 s0, 0x120000
	v_pk_mul_f32 v[46:47], v[40:41], v[40:41]
	v_pk_mul_f32 v[54:55], v[42:43], v[42:43]
	v_cvt_pk_bf16_f32 v40, v44, v45
	v_add_co_u32_e32 v44, vcc, s0, v128
	v_pk_fma_f32 v[32:33], v[32:33], v[48:49], 0 op_sel_hi:[1,0,0]
	v_cvt_pk_bf16_f32 v41, v46, v47
	v_cvt_pk_bf16_f32 v42, v52, v53
	v_cvt_pk_bf16_f32 v43, v54, v55
	v_addc_co_u32_e32 v45, vcc, 0, v129, vcc
	v_pk_fma_f32 v[38:39], v[38:39], v[48:49], 0 op_sel_hi:[1,0,0]
	v_max_f32_e32 v32, 0, v32
	v_max_f32_e32 v33, 0, v33
	global_store_dwordx4 v[44:45], v[40:43], off
	v_pk_fma_f32 v[34:35], v[34:35], v[48:49], 0 op_sel_hi:[1,0,0]
	v_pk_fma_f32 v[36:37], v[36:37], v[48:49], 0 op_sel_hi:[1,0,0]
	v_pk_mul_f32 v[40:41], v[32:33], v[32:33]
	v_max_f32_e32 v32, 0, v38
	v_max_f32_e32 v33, 0, v39
	v_pk_mul_f32 v[38:39], v[32:33], v[32:33]
	v_fmamk_f32 v32, v148, 0x3a800000, v145
	v_max_f32_e32 v34, 0, v34
	v_max_f32_e32 v35, 0, v35
	v_rsq_f32_e32 v44, v32
	v_pk_mul_f32 v[42:43], v[34:35], v[34:35]
	v_max_f32_e32 v36, 0, v36
	v_max_f32_e32 v37, 0, v37
	v_pk_mul_f32 v[36:37], v[36:37], v[36:37]
	v_cvt_pk_bf16_f32 v32, v36, v37
	v_cvt_pk_bf16_f32 v33, v38, v39
	s_nop 0
	v_cvt_pk_bf16_f32 v35, v42, v43
	s_nop 0
	v_mov_b32_e32 v36, v44
	v_cvt_pk_bf16_f32 v34, v40, v41
	global_store_dwordx4 v[50:51], v[32:35], off offset:256
	s_mov_b64 s[0:1], 0x140000
	s_nop 0
	v_mov_b32_e32 v32, v36
	v_pk_fma_f32 v[28:29], v[28:29], v[32:33], 0 op_sel_hi:[1,0,0]
	v_pk_fma_f32 v[24:25], v[24:25], v[32:33], 0 op_sel_hi:[1,0,0]
	v_pk_fma_f32 v[30:31], v[30:31], v[32:33], 0 op_sel_hi:[1,0,0]
	v_pk_fma_f32 v[26:27], v[26:27], v[32:33], 0 op_sel_hi:[1,0,0]
	v_max_f32_e32 v28, 0, v28
	v_max_f32_e32 v24, 0, v24
	v_max_f32_e32 v29, 0, v29
	v_max_f32_e32 v25, 0, v25
	v_lshl_add_u64 v[34:35], v[128:129], 0, s[0:1]
	v_pk_mul_f32 v[28:29], v[28:29], v[28:29]
	v_pk_mul_f32 v[36:37], v[24:25], v[24:25]
	v_max_f32_e32 v24, 0, v30
	v_max_f32_e32 v26, 0, v26
	v_max_f32_e32 v25, 0, v31
	v_max_f32_e32 v27, 0, v27
	s_mov_b32 s0, 0x140000
	v_pk_mul_f32 v[30:31], v[24:25], v[24:25]
	v_pk_mul_f32 v[38:39], v[26:27], v[26:27]
	v_cvt_pk_bf16_f32 v24, v28, v29
	v_add_co_u32_e32 v28, vcc, s0, v128
	v_pk_fma_f32 v[16:17], v[16:17], v[32:33], 0 op_sel_hi:[1,0,0]
	v_cvt_pk_bf16_f32 v25, v30, v31
	v_cvt_pk_bf16_f32 v26, v36, v37
	v_cvt_pk_bf16_f32 v27, v38, v39
	v_addc_co_u32_e32 v29, vcc, 0, v129, vcc
	v_pk_fma_f32 v[22:23], v[22:23], v[32:33], 0 op_sel_hi:[1,0,0]
	v_max_f32_e32 v16, 0, v16
	v_max_f32_e32 v17, 0, v17
	global_store_dwordx4 v[28:29], v[24:27], off
	v_pk_fma_f32 v[18:19], v[18:19], v[32:33], 0 op_sel_hi:[1,0,0]
	v_pk_fma_f32 v[20:21], v[20:21], v[32:33], 0 op_sel_hi:[1,0,0]
	v_pk_mul_f32 v[24:25], v[16:17], v[16:17]
	v_max_f32_e32 v16, 0, v22
	v_max_f32_e32 v17, 0, v23
	v_pk_mul_f32 v[22:23], v[16:17], v[16:17]
	v_fmamk_f32 v16, v147, 0x3a800000, v145
	v_max_f32_e32 v18, 0, v18
	v_max_f32_e32 v19, 0, v19
	v_rsq_f32_e32 v28, v16
	v_pk_mul_f32 v[26:27], v[18:19], v[18:19]
	v_max_f32_e32 v20, 0, v20
	v_max_f32_e32 v21, 0, v21
	v_pk_mul_f32 v[20:21], v[20:21], v[20:21]
	v_cvt_pk_bf16_f32 v16, v20, v21
	v_cvt_pk_bf16_f32 v17, v22, v23
	s_nop 0
	v_cvt_pk_bf16_f32 v19, v26, v27
	s_nop 0
	v_mov_b32_e32 v20, v28
	v_cvt_pk_bf16_f32 v18, v24, v25
	global_store_dwordx4 v[34:35], v[16:19], off offset:256
	s_mov_b64 s[0:1], 0x160000
	s_nop 0
	v_mov_b32_e32 v16, v20
	v_pk_fma_f32 v[12:13], v[12:13], v[16:17], 0 op_sel_hi:[1,0,0]
	v_pk_fma_f32 v[8:9], v[8:9], v[16:17], 0 op_sel_hi:[1,0,0]
	v_pk_fma_f32 v[14:15], v[14:15], v[16:17], 0 op_sel_hi:[1,0,0]
	v_pk_fma_f32 v[10:11], v[10:11], v[16:17], 0 op_sel_hi:[1,0,0]
	v_max_f32_e32 v12, 0, v12
	v_max_f32_e32 v8, 0, v8
	v_max_f32_e32 v13, 0, v13
	v_max_f32_e32 v9, 0, v9
	v_lshl_add_u64 v[18:19], v[128:129], 0, s[0:1]
	v_pk_mul_f32 v[12:13], v[12:13], v[12:13]
	v_pk_mul_f32 v[20:21], v[8:9], v[8:9]
	v_max_f32_e32 v8, 0, v14
	v_max_f32_e32 v10, 0, v10
	v_max_f32_e32 v9, 0, v15
	v_max_f32_e32 v11, 0, v11
	s_mov_b32 s0, 0x160000
	v_pk_mul_f32 v[14:15], v[8:9], v[8:9]
	v_pk_mul_f32 v[22:23], v[10:11], v[10:11]
	v_cvt_pk_bf16_f32 v8, v12, v13
	v_add_co_u32_e32 v12, vcc, s0, v128
	v_pk_fma_f32 v[0:1], v[0:1], v[16:17], 0 op_sel_hi:[1,0,0]
	v_cvt_pk_bf16_f32 v9, v14, v15
	v_cvt_pk_bf16_f32 v10, v20, v21
	v_cvt_pk_bf16_f32 v11, v22, v23
	v_addc_co_u32_e32 v13, vcc, 0, v129, vcc
	v_pk_fma_f32 v[6:7], v[6:7], v[16:17], 0 op_sel_hi:[1,0,0]
	v_pk_fma_f32 v[4:5], v[4:5], v[16:17], 0 op_sel_hi:[1,0,0]
	v_pk_fma_f32 v[2:3], v[2:3], v[16:17], 0 op_sel_hi:[1,0,0]
	v_max_f32_e32 v0, 0, v0
	v_max_f32_e32 v1, 0, v1
	global_store_dwordx4 v[12:13], v[8:11], off
	v_max_f32_e32 v4, 0, v4
	v_max_f32_e32 v5, 0, v5
	v_pk_mul_f32 v[8:9], v[0:1], v[0:1]
	v_max_f32_e32 v0, 0, v6
	v_max_f32_e32 v2, 0, v2
	v_max_f32_e32 v1, 0, v7
	v_max_f32_e32 v3, 0, v3
	v_pk_mul_f32 v[4:5], v[4:5], v[4:5]
	v_pk_mul_f32 v[6:7], v[0:1], v[0:1]
	v_pk_mul_f32 v[10:11], v[2:3], v[2:3]
	v_cvt_pk_bf16_f32 v0, v4, v5
	v_cvt_pk_bf16_f32 v1, v6, v7
	v_cvt_pk_bf16_f32 v2, v8, v9
	v_cvt_pk_bf16_f32 v3, v10, v11
	s_mov_b64 s[0:1], -1
	global_store_dwordx4 v[18:19], v[0:3], off offset:256
	s_cbranch_scc1 .LBB0_659
	s_andn2_b64 vcc, exec, s[20:21]
	s_cbranch_vccnz .LBB0_658
	s_barrier
	s_branch .LBB0_658

.LBB0_997:
	v_lshl_add_u32 v128, s71, 8, v141
	v_ashrrev_i32_e32 v129, 31, v128
	v_lshl_add_u64 v[164:165], v[128:129], 2, s[10:11]
	v_or_b32_e32 v136, 16, v128
	global_load_dword v170, v[164:165], off
	v_ashrrev_i32_e32 v137, 31, v136
	v_lshl_add_u64 v[130:131], v[136:137], 2, s[10:11]
	global_load_dword v171, v[130:131], off
	v_or_b32_e32 v130, 48, v128
	v_or_b32_e32 v134, 32, v128
	v_ashrrev_i32_e32 v131, 31, v130
	v_ashrrev_i32_e32 v135, 31, v134
	v_lshl_add_u64 v[168:169], v[130:131], 2, s[10:11]
	v_lshl_add_u64 v[166:167], v[134:135], 2, s[10:11]
	global_load_dword v172, v[164:165], off offset:512
	global_load_dword v151, v[164:165], off offset:576
	global_load_dword v150, v[164:165], off offset:640
	global_load_dword v173, v[166:167], off
	s_nop 0
	global_load_dword v168, v[168:169], off
	s_nop 0
	global_load_dword v149, v[164:165], off offset:704
	v_lshl_or_b32 v132, s70, 8, v143
	v_ashrrev_i32_e32 v133, 31, v132
	v_lshlrev_b64 v[128:129], 13, v[128:129]
	v_lshlrev_b64 v[132:133], 1, v[132:133]
	v_lshl_add_u64 v[128:129], s[14:15], 0, v[128:129]
	v_lshl_add_u64 v[128:129], v[128:129], 0, v[132:133]
	s_cmp_eq_u32 s69, 3
	s_waitcnt vmcnt(0)
	v_fmamk_f32 v164, v170, 0x3a800000, v147
	v_fmamk_f32 v166, v171, 0x3a800000, v147
	v_rsq_f32_e32 v164, v164
	v_rsq_f32_e32 v171, v166
	v_pk_fma_f32 v[126:127], v[126:127], v[164:165], 0 op_sel_hi:[1,0,0]
	v_pk_fma_f32 v[124:125], v[124:125], v[164:165], 0 op_sel_hi:[1,0,0]
	v_pk_fma_f32 v[122:123], v[122:123], v[164:165], 0 op_sel_hi:[1,0,0]
	v_pk_fma_f32 v[120:121], v[120:121], v[164:165], 0 op_sel_hi:[1,0,0]
	v_pk_fma_f32 v[114:115], v[114:115], v[164:165], 0 op_sel_hi:[1,0,0]
	v_pk_fma_f32 v[112:113], v[112:113], v[164:165], 0 op_sel_hi:[1,0,0]
	v_max_f32_e32 v124, 0, v124
	v_max_f32_e32 v120, 0, v120
	v_max_f32_e32 v125, 0, v125
	v_max_f32_e32 v121, 0, v121
	v_max_f32_e32 v126, 0, v126
	v_max_f32_e32 v122, 0, v122
	v_max_f32_e32 v127, 0, v127
	v_max_f32_e32 v123, 0, v123
	v_max_f32_e32 v112, 0, v112
	v_max_f32_e32 v113, 0, v113
	v_max_f32_e32 v114, 0, v114
	v_max_f32_e32 v115, 0, v115
	v_pk_mul_f32 v[124:125], v[124:125], v[124:125]
	v_pk_mul_f32 v[120:121], v[120:121], v[120:121]
	v_pk_mul_f32 v[126:127], v[126:127], v[126:127]
	v_pk_mul_f32 v[122:123], v[122:123], v[122:123]
	v_pk_fma_f32 v[118:119], v[118:119], v[164:165], 0 op_sel_hi:[1,0,0]
	v_pk_fma_f32 v[116:117], v[116:117], v[164:165], 0 op_sel_hi:[1,0,0]
	v_pk_mul_f32 v[164:165], v[112:113], v[112:113]
	v_pk_mul_f32 v[166:167], v[114:115], v[114:115]
	v_cvt_pk_bf16_f32 v112, v124, v125
	v_cvt_pk_bf16_f32 v113, v126, v127
	v_cvt_pk_bf16_f32 v114, v120, v121
	v_cvt_pk_bf16_f32 v115, v122, v123
	global_store_dwordx4 v[128:129], v[112:115], off
	v_max_f32_e32 v116, 0, v116
	v_max_f32_e32 v117, 0, v117
	v_max_f32_e32 v118, 0, v118
	v_max_f32_e32 v119, 0, v119
	v_pk_mul_f32 v[116:117], v[116:117], v[116:117]
	v_mov_b32_e32 v112, v171
	v_pk_mul_f32 v[118:119], v[118:119], v[118:119]
	v_pk_fma_f32 v[104:105], v[104:105], v[112:113], 0 op_sel_hi:[1,0,0]
	v_cvt_pk_bf16_f32 v116, v116, v117
	v_cvt_pk_bf16_f32 v117, v118, v119
	v_cvt_pk_bf16_f32 v118, v164, v165
	v_cvt_pk_bf16_f32 v119, v166, v167
	v_pk_fma_f32 v[110:111], v[110:111], v[112:113], 0 op_sel_hi:[1,0,0]
	v_pk_fma_f32 v[108:109], v[108:109], v[112:113], 0 op_sel_hi:[1,0,0]
	v_pk_fma_f32 v[106:107], v[106:107], v[112:113], 0 op_sel_hi:[1,0,0]
	v_max_f32_e32 v104, 0, v104
	v_max_f32_e32 v105, 0, v105
	global_store_dwordx4 v[128:129], v[116:119], off offset:256
	v_lshlrev_b64 v[114:115], 13, v[136:137]
	v_max_f32_e32 v108, 0, v108
	v_max_f32_e32 v109, 0, v109
	v_pk_mul_f32 v[116:117], v[104:105], v[104:105]
	v_max_f32_e32 v104, 0, v110
	v_max_f32_e32 v106, 0, v106
	v_max_f32_e32 v105, 0, v111
	v_max_f32_e32 v107, 0, v107
	v_lshl_add_u64 v[114:115], s[14:15], 0, v[114:115]
	v_pk_mul_f32 v[108:109], v[108:109], v[108:109]
	v_pk_mul_f32 v[110:111], v[104:105], v[104:105]
	v_pk_mul_f32 v[118:119], v[106:107], v[106:107]
	v_pk_fma_f32 v[96:97], v[96:97], v[112:113], 0 op_sel_hi:[1,0,0]
	v_lshl_add_u64 v[114:115], v[114:115], 0, v[132:133]
	v_cvt_pk_bf16_f32 v104, v108, v109
	v_cvt_pk_bf16_f32 v105, v110, v111
	v_cvt_pk_bf16_f32 v106, v116, v117
	v_cvt_pk_bf16_f32 v107, v118, v119
	v_pk_fma_f32 v[102:103], v[102:103], v[112:113], 0 op_sel_hi:[1,0,0]
	v_max_f32_e32 v96, 0, v96
	v_max_f32_e32 v97, 0, v97
	global_store_dwordx4 v[114:115], v[104:107], off
	v_pk_fma_f32 v[98:99], v[98:99], v[112:113], 0 op_sel_hi:[1,0,0]
	v_pk_fma_f32 v[100:101], v[100:101], v[112:113], 0 op_sel_hi:[1,0,0]
	v_pk_mul_f32 v[104:105], v[96:97], v[96:97]
	v_max_f32_e32 v96, 0, v102
	v_max_f32_e32 v97, 0, v103
	v_pk_mul_f32 v[102:103], v[96:97], v[96:97]
	v_fmamk_f32 v96, v173, 0x3a800000, v147
	v_max_f32_e32 v98, 0, v98
	v_max_f32_e32 v99, 0, v99
	v_rsq_f32_e32 v108, v96
	v_pk_mul_f32 v[106:107], v[98:99], v[98:99]
	v_max_f32_e32 v100, 0, v100
	v_max_f32_e32 v101, 0, v101
	v_pk_mul_f32 v[100:101], v[100:101], v[100:101]
	v_cvt_pk_bf16_f32 v96, v100, v101
	v_cvt_pk_bf16_f32 v97, v102, v103
	s_nop 0
	v_cvt_pk_bf16_f32 v99, v106, v107
	s_nop 0
	v_mov_b32_e32 v100, v108
	v_cvt_pk_bf16_f32 v98, v104, v105
	global_store_dwordx4 v[114:115], v[96:99], off offset:256
	s_nop 1
	v_mov_b32_e32 v96, v100
	v_pk_fma_f32 v[88:89], v[88:89], v[96:97], 0 op_sel_hi:[1,0,0]
	v_pk_fma_f32 v[94:95], v[94:95], v[96:97], 0 op_sel_hi:[1,0,0]
	v_pk_fma_f32 v[92:93], v[92:93], v[96:97], 0 op_sel_hi:[1,0,0]
	v_pk_fma_f32 v[90:91], v[90:91], v[96:97], 0 op_sel_hi:[1,0,0]
	v_max_f32_e32 v88, 0, v88
	v_max_f32_e32 v89, 0, v89
	v_lshlrev_b64 v[98:99], 13, v[134:135]
	v_max_f32_e32 v92, 0, v92
	v_max_f32_e32 v93, 0, v93
	v_pk_mul_f32 v[100:101], v[88:89], v[88:89]
	v_max_f32_e32 v88, 0, v94
	v_max_f32_e32 v90, 0, v90
	v_max_f32_e32 v89, 0, v95
	v_max_f32_e32 v91, 0, v91
	v_lshl_add_u64 v[98:99], s[14:15], 0, v[98:99]
	v_pk_mul_f32 v[92:93], v[92:93], v[92:93]
	v_pk_mul_f32 v[94:95], v[88:89], v[88:89]
	v_pk_mul_f32 v[102:103], v[90:91], v[90:91]
	v_pk_fma_f32 v[80:81], v[80:81], v[96:97], 0 op_sel_hi:[1,0,0]
	v_lshl_add_u64 v[98:99], v[98:99], 0, v[132:133]
	v_cvt_pk_bf16_f32 v88, v92, v93
	v_cvt_pk_bf16_f32 v89, v94, v95
	v_cvt_pk_bf16_f32 v90, v100, v101
	v_cvt_pk_bf16_f32 v91, v102, v103
	v_pk_fma_f32 v[86:87], v[86:87], v[96:97], 0 op_sel_hi:[1,0,0]
	v_max_f32_e32 v80, 0, v80
	v_max_f32_e32 v81, 0, v81
	global_store_dwordx4 v[98:99], v[88:91], off
	v_pk_fma_f32 v[82:83], v[82:83], v[96:97], 0 op_sel_hi:[1,0,0]
	v_pk_fma_f32 v[84:85], v[84:85], v[96:97], 0 op_sel_hi:[1,0,0]
	v_pk_mul_f32 v[88:89], v[80:81], v[80:81]
	v_max_f32_e32 v80, 0, v86
	v_max_f32_e32 v81, 0, v87
	v_pk_mul_f32 v[86:87], v[80:81], v[80:81]
	v_fmamk_f32 v80, v168, 0x3a800000, v147
	v_max_f32_e32 v82, 0, v82
	v_max_f32_e32 v83, 0, v83
	v_rsq_f32_e32 v92, v80
	v_pk_mul_f32 v[90:91], v[82:83], v[82:83]
	v_max_f32_e32 v84, 0, v84
	v_max_f32_e32 v85, 0, v85
	v_pk_mul_f32 v[84:85], v[84:85], v[84:85]
	v_cvt_pk_bf16_f32 v80, v84, v85
	v_cvt_pk_bf16_f32 v81, v86, v87
	s_nop 0
	v_cvt_pk_bf16_f32 v83, v90, v91
	s_nop 0
	v_mov_b32_e32 v84, v92
	v_cvt_pk_bf16_f32 v82, v88, v89
	global_store_dwordx4 v[98:99], v[80:83], off offset:256
	s_nop 1
	v_mov_b32_e32 v80, v84
	v_pk_fma_f32 v[72:73], v[72:73], v[80:81], 0 op_sel_hi:[1,0,0]
	v_pk_fma_f32 v[78:79], v[78:79], v[80:81], 0 op_sel_hi:[1,0,0]
	v_pk_fma_f32 v[76:77], v[76:77], v[80:81], 0 op_sel_hi:[1,0,0]
	v_pk_fma_f32 v[74:75], v[74:75], v[80:81], 0 op_sel_hi:[1,0,0]
	v_max_f32_e32 v72, 0, v72
	v_max_f32_e32 v73, 0, v73
	v_lshlrev_b64 v[82:83], 13, v[130:131]
	v_max_f32_e32 v76, 0, v76
	v_max_f32_e32 v77, 0, v77
	v_pk_mul_f32 v[84:85], v[72:73], v[72:73]
	v_max_f32_e32 v72, 0, v78
	v_max_f32_e32 v74, 0, v74
	v_max_f32_e32 v73, 0, v79
	v_max_f32_e32 v75, 0, v75
	v_lshl_add_u64 v[82:83], s[14:15], 0, v[82:83]
	v_pk_mul_f32 v[76:77], v[76:77], v[76:77]
	v_pk_mul_f32 v[78:79], v[72:73], v[72:73]
	v_pk_mul_f32 v[86:87], v[74:75], v[74:75]
	v_pk_fma_f32 v[64:65], v[64:65], v[80:81], 0 op_sel_hi:[1,0,0]
	v_lshl_add_u64 v[82:83], v[82:83], 0, v[132:133]
	v_cvt_pk_bf16_f32 v72, v76, v77
	v_cvt_pk_bf16_f32 v73, v78, v79
	v_cvt_pk_bf16_f32 v74, v84, v85
	v_cvt_pk_bf16_f32 v75, v86, v87
	v_pk_fma_f32 v[70:71], v[70:71], v[80:81], 0 op_sel_hi:[1,0,0]
	v_max_f32_e32 v64, 0, v64
	v_max_f32_e32 v65, 0, v65
	global_store_dwordx4 v[82:83], v[72:75], off
	v_pk_fma_f32 v[66:67], v[66:67], v[80:81], 0 op_sel_hi:[1,0,0]
	v_pk_fma_f32 v[68:69], v[68:69], v[80:81], 0 op_sel_hi:[1,0,0]
	v_pk_mul_f32 v[72:73], v[64:65], v[64:65]
	v_max_f32_e32 v64, 0, v70
	v_max_f32_e32 v65, 0, v71
	v_pk_mul_f32 v[70:71], v[64:65], v[64:65]
	v_fmamk_f32 v64, v172, 0x3a800000, v147
	v_max_f32_e32 v66, 0, v66
	v_max_f32_e32 v67, 0, v67
	v_rsq_f32_e32 v76, v64
	v_pk_mul_f32 v[74:75], v[66:67], v[66:67]
	v_max_f32_e32 v68, 0, v68
	v_max_f32_e32 v69, 0, v69
	v_pk_mul_f32 v[68:69], v[68:69], v[68:69]
	v_cvt_pk_bf16_f32 v64, v68, v69
	v_cvt_pk_bf16_f32 v65, v70, v71
	s_nop 0
	v_cvt_pk_bf16_f32 v67, v74, v75
	s_nop 0
	v_mov_b32_e32 v68, v76
	v_cvt_pk_bf16_f32 v66, v72, v73
	global_store_dwordx4 v[82:83], v[64:67], off offset:256
	s_nop 1
	v_mov_b32_e32 v64, v68
	v_pk_fma_f32 v[60:61], v[60:61], v[64:65], 0 op_sel_hi:[1,0,0]
	v_pk_fma_f32 v[56:57], v[56:57], v[64:65], 0 op_sel_hi:[1,0,0]
	v_pk_fma_f32 v[62:63], v[62:63], v[64:65], 0 op_sel_hi:[1,0,0]
	v_pk_fma_f32 v[58:59], v[58:59], v[64:65], 0 op_sel_hi:[1,0,0]
	v_max_f32_e32 v60, 0, v60
	v_max_f32_e32 v56, 0, v56
	v_max_f32_e32 v61, 0, v61
	v_max_f32_e32 v57, 0, v57
	v_pk_mul_f32 v[60:61], v[60:61], v[60:61]
	v_pk_mul_f32 v[68:69], v[56:57], v[56:57]
	v_max_f32_e32 v56, 0, v62
	v_max_f32_e32 v58, 0, v58
	v_max_f32_e32 v57, 0, v63
	v_max_f32_e32 v59, 0, v59
	v_pk_mul_f32 v[62:63], v[56:57], v[56:57]
	v_pk_mul_f32 v[70:71], v[58:59], v[58:59]
	v_cvt_pk_bf16_f32 v56, v60, v61
	v_add_co_u32_e32 v60, vcc, s65, v128
	v_pk_fma_f32 v[48:49], v[48:49], v[64:65], 0 op_sel_hi:[1,0,0]
	v_cvt_pk_bf16_f32 v57, v62, v63
	v_cvt_pk_bf16_f32 v58, v68, v69
	v_cvt_pk_bf16_f32 v59, v70, v71
	v_addc_co_u32_e32 v61, vcc, 0, v129, vcc
	v_pk_fma_f32 v[54:55], v[54:55], v[64:65], 0 op_sel_hi:[1,0,0]
	v_max_f32_e32 v48, 0, v48
	v_max_f32_e32 v49, 0, v49
	global_store_dwordx4 v[60:61], v[56:59], off
	v_pk_fma_f32 v[50:51], v[50:51], v[64:65], 0 op_sel_hi:[1,0,0]
	v_pk_fma_f32 v[52:53], v[52:53], v[64:65], 0 op_sel_hi:[1,0,0]
	v_pk_mul_f32 v[56:57], v[48:49], v[48:49]
	v_max_f32_e32 v48, 0, v54
	v_max_f32_e32 v49, 0, v55
	v_pk_mul_f32 v[54:55], v[48:49], v[48:49]
	v_fmamk_f32 v48, v151, 0x3a800000, v147
	v_max_f32_e32 v50, 0, v50
	v_max_f32_e32 v51, 0, v51
	v_rsq_f32_e32 v60, v48
	v_pk_mul_f32 v[58:59], v[50:51], v[50:51]
	v_max_f32_e32 v52, 0, v52
	v_max_f32_e32 v53, 0, v53
	v_pk_mul_f32 v[52:53], v[52:53], v[52:53]
	v_cvt_pk_bf16_f32 v48, v52, v53
	v_cvt_pk_bf16_f32 v49, v54, v55
	v_lshl_add_u64 v[66:67], v[128:129], 0, s[26:27]
	v_cvt_pk_bf16_f32 v51, v58, v59
	s_nop 0
	v_mov_b32_e32 v52, v60
	v_cvt_pk_bf16_f32 v50, v56, v57
	global_store_dwordx4 v[66:67], v[48:51], off offset:256
	s_nop 1
	v_mov_b32_e32 v48, v52
	v_pk_fma_f32 v[44:45], v[44:45], v[48:49], 0 op_sel_hi:[1,0,0]
	v_pk_fma_f32 v[40:41], v[40:41], v[48:49], 0 op_sel_hi:[1,0,0]
	v_pk_fma_f32 v[46:47], v[46:47], v[48:49], 0 op_sel_hi:[1,0,0]
	v_pk_fma_f32 v[42:43], v[42:43], v[48:49], 0 op_sel_hi:[1,0,0]
	v_max_f32_e32 v44, 0, v44
	v_max_f32_e32 v40, 0, v40
	v_max_f32_e32 v45, 0, v45
	v_max_f32_e32 v41, 0, v41
	v_pk_mul_f32 v[44:45], v[44:45], v[44:45]
	v_pk_mul_f32 v[52:53], v[40:41], v[40:41]
	v_max_f32_e32 v40, 0, v46
	v_max_f32_e32 v42, 0, v42
	v_max_f32_e32 v41, 0, v47
	v_max_f32_e32 v43, 0, v43
	v_pk_mul_f32 v[46:47], v[40:41], v[40:41]
	v_pk_mul_f32 v[54:55], v[42:43], v[42:43]
	v_cvt_pk_bf16_f32 v40, v44, v45
	v_add_co_u32_e32 v44, vcc, s66, v128
	v_pk_fma_f32 v[32:33], v[32:33], v[48:49], 0 op_sel_hi:[1,0,0]
	v_cvt_pk_bf16_f32 v41, v46, v47
	v_cvt_pk_bf16_f32 v42, v52, v53
	v_cvt_pk_bf16_f32 v43, v54, v55
	v_addc_co_u32_e32 v45, vcc, 0, v129, vcc
	v_pk_fma_f32 v[38:39], v[38:39], v[48:49], 0 op_sel_hi:[1,0,0]
	v_max_f32_e32 v32, 0, v32
	v_max_f32_e32 v33, 0, v33
	global_store_dwordx4 v[44:45], v[40:43], off
	v_pk_fma_f32 v[34:35], v[34:35], v[48:49], 0 op_sel_hi:[1,0,0]
	v_pk_fma_f32 v[36:37], v[36:37], v[48:49], 0 op_sel_hi:[1,0,0]
	v_pk_mul_f32 v[40:41], v[32:33], v[32:33]
	v_max_f32_e32 v32, 0, v38
	v_max_f32_e32 v33, 0, v39
	v_pk_mul_f32 v[38:39], v[32:33], v[32:33]
	v_fmamk_f32 v32, v150, 0x3a800000, v147
	v_max_f32_e32 v34, 0, v34
	v_max_f32_e32 v35, 0, v35
	v_rsq_f32_e32 v44, v32
	v_pk_mul_f32 v[42:43], v[34:35], v[34:35]
	v_max_f32_e32 v36, 0, v36
	v_max_f32_e32 v37, 0, v37
	v_pk_mul_f32 v[36:37], v[36:37], v[36:37]
	v_cvt_pk_bf16_f32 v32, v36, v37
	v_cvt_pk_bf16_f32 v33, v38, v39
	v_lshl_add_u64 v[50:51], v[128:129], 0, s[28:29]
	v_cvt_pk_bf16_f32 v35, v42, v43
	s_nop 0
	v_mov_b32_e32 v36, v44
	v_cvt_pk_bf16_f32 v34, v40, v41
	global_store_dwordx4 v[50:51], v[32:35], off offset:256
	s_nop 1
	v_mov_b32_e32 v32, v36
	v_pk_fma_f32 v[28:29], v[28:29], v[32:33], 0 op_sel_hi:[1,0,0]
	v_pk_fma_f32 v[24:25], v[24:25], v[32:33], 0 op_sel_hi:[1,0,0]
	v_pk_fma_f32 v[30:31], v[30:31], v[32:33], 0 op_sel_hi:[1,0,0]
	v_pk_fma_f32 v[26:27], v[26:27], v[32:33], 0 op_sel_hi:[1,0,0]
	v_max_f32_e32 v28, 0, v28
	v_max_f32_e32 v24, 0, v24
	v_max_f32_e32 v29, 0, v29
	v_max_f32_e32 v25, 0, v25
	v_pk_mul_f32 v[28:29], v[28:29], v[28:29]
	v_pk_mul_f32 v[36:37], v[24:25], v[24:25]
	v_max_f32_e32 v24, 0, v30
	v_max_f32_e32 v26, 0, v26
	v_max_f32_e32 v25, 0, v31
	v_max_f32_e32 v27, 0, v27
	v_pk_mul_f32 v[30:31], v[24:25], v[24:25]
	v_pk_mul_f32 v[38:39], v[26:27], v[26:27]
	v_cvt_pk_bf16_f32 v24, v28, v29
	v_add_co_u32_e32 v28, vcc, s67, v128
	v_pk_fma_f32 v[16:17], v[16:17], v[32:33], 0 op_sel_hi:[1,0,0]
	v_cvt_pk_bf16_f32 v25, v30, v31
	v_cvt_pk_bf16_f32 v26, v36, v37
	v_cvt_pk_bf16_f32 v27, v38, v39
	v_addc_co_u32_e32 v29, vcc, 0, v129, vcc
	v_pk_fma_f32 v[22:23], v[22:23], v[32:33], 0 op_sel_hi:[1,0,0]
	v_max_f32_e32 v16, 0, v16
	v_max_f32_e32 v17, 0, v17
	global_store_dwordx4 v[28:29], v[24:27], off
	v_pk_fma_f32 v[18:19], v[18:19], v[32:33], 0 op_sel_hi:[1,0,0]
	v_pk_fma_f32 v[20:21], v[20:21], v[32:33], 0 op_sel_hi:[1,0,0]
	v_pk_mul_f32 v[24:25], v[16:17], v[16:17]
	v_max_f32_e32 v16, 0, v22
	v_max_f32_e32 v17, 0, v23
	v_pk_mul_f32 v[22:23], v[16:17], v[16:17]
	v_fmamk_f32 v16, v149, 0x3a800000, v147
	v_max_f32_e32 v18, 0, v18
	v_max_f32_e32 v19, 0, v19
	v_rsq_f32_e32 v28, v16
	v_pk_mul_f32 v[26:27], v[18:19], v[18:19]
	v_max_f32_e32 v20, 0, v20
	v_max_f32_e32 v21, 0, v21
	v_pk_mul_f32 v[20:21], v[20:21], v[20:21]
	v_cvt_pk_bf16_f32 v16, v20, v21
	v_cvt_pk_bf16_f32 v17, v22, v23
	v_lshl_add_u64 v[34:35], v[128:129], 0, s[30:31]
	v_cvt_pk_bf16_f32 v19, v26, v27
	s_nop 0
	v_mov_b32_e32 v20, v28
	v_cvt_pk_bf16_f32 v18, v24, v25
	global_store_dwordx4 v[34:35], v[16:19], off offset:256
	s_mov_b64 s[0:1], -1
	s_nop 0
	v_mov_b32_e32 v16, v20
	v_pk_fma_f32 v[12:13], v[12:13], v[16:17], 0 op_sel_hi:[1,0,0]
	v_pk_fma_f32 v[8:9], v[8:9], v[16:17], 0 op_sel_hi:[1,0,0]
	v_pk_fma_f32 v[14:15], v[14:15], v[16:17], 0 op_sel_hi:[1,0,0]
	v_pk_fma_f32 v[10:11], v[10:11], v[16:17], 0 op_sel_hi:[1,0,0]
	v_max_f32_e32 v12, 0, v12
	v_max_f32_e32 v8, 0, v8
	v_max_f32_e32 v13, 0, v13
	v_max_f32_e32 v9, 0, v9
	v_pk_mul_f32 v[12:13], v[12:13], v[12:13]
	v_pk_mul_f32 v[20:21], v[8:9], v[8:9]
	v_max_f32_e32 v8, 0, v14
	v_max_f32_e32 v10, 0, v10
	v_max_f32_e32 v9, 0, v15
	v_max_f32_e32 v11, 0, v11
	v_pk_mul_f32 v[14:15], v[8:9], v[8:9]
	v_pk_mul_f32 v[22:23], v[10:11], v[10:11]
	v_cvt_pk_bf16_f32 v8, v12, v13
	v_add_co_u32_e32 v12, vcc, s68, v128
	v_pk_fma_f32 v[0:1], v[0:1], v[16:17], 0 op_sel_hi:[1,0,0]
	v_cvt_pk_bf16_f32 v9, v14, v15
	v_cvt_pk_bf16_f32 v10, v20, v21
	v_cvt_pk_bf16_f32 v11, v22, v23
	v_addc_co_u32_e32 v13, vcc, 0, v129, vcc
	v_pk_fma_f32 v[6:7], v[6:7], v[16:17], 0 op_sel_hi:[1,0,0]
	v_pk_fma_f32 v[4:5], v[4:5], v[16:17], 0 op_sel_hi:[1,0,0]
	v_pk_fma_f32 v[2:3], v[2:3], v[16:17], 0 op_sel_hi:[1,0,0]
	v_max_f32_e32 v0, 0, v0
	v_max_f32_e32 v1, 0, v1
	global_store_dwordx4 v[12:13], v[8:11], off
	v_max_f32_e32 v4, 0, v4
	v_max_f32_e32 v5, 0, v5
	v_pk_mul_f32 v[8:9], v[0:1], v[0:1]
	v_max_f32_e32 v0, 0, v6
	v_max_f32_e32 v2, 0, v2
	v_max_f32_e32 v1, 0, v7
	v_max_f32_e32 v3, 0, v3
	v_pk_mul_f32 v[4:5], v[4:5], v[4:5]
	v_pk_mul_f32 v[6:7], v[0:1], v[0:1]
	v_pk_mul_f32 v[10:11], v[2:3], v[2:3]
	v_lshl_add_u64 v[18:19], v[128:129], 0, s[34:35]
	v_cvt_pk_bf16_f32 v0, v4, v5
	v_cvt_pk_bf16_f32 v1, v6, v7
	v_cvt_pk_bf16_f32 v2, v8, v9
	v_cvt_pk_bf16_f32 v3, v10, v11
	global_store_dwordx4 v[18:19], v[0:3], off offset:256
	s_cbranch_scc1 .LBB0_992
	s_andn2_b64 vcc, exec, s[20:21]
	s_cbranch_vccnz .LBB0_991
	s_barrier
	s_branch .LBB0_991
